# s5_fill BtY state columns: the eight A-power loads of an element issued together instead of five load-wait rounds
# speedup vs baseline: 1.0022x; 1.0022x over previous
; DEVI unsigned cvt_pk(float lo, float hi) { f32v2_t f = {lo, hi}; bf16v2_t v = __builtin_convertvector(f, bf16v2_t); return __builtin_bit_cast(unsigned, v); }
; DEVI void s5_fill(const Params& p) {
;     ...
;     for (int e = gt; e < 64 * 512 * 80; e += nthr) { const int k8 = (e % 80) * 8, n = (e / 80) & 511, g = e / (80 * 512), t = n >> 4, hh = n & 15; float v[8];
;         if (k8 < 512) { const int s = k8 >> 4, h0 = k8 & 15;
; #pragma unroll
;             for (int j = 0; j < 8; ++j) { float x = 0.f; if (s <= t) { x = kc[(((size_t)g * 32 + (t - s)) * 16 + hh) * 16 + h0 + j]; if (s == t && h0 + j == hh) x += p.in[25][g * 16 + hh]; } v[j] = x; }
;         } else { const int q0 = k8 - 512;
; #pragma unroll
;             for (int j = 0; j < 8; ++j) { const int q = q0 + j, pp = q & 63; const size_t gp = (size_t)g * 64 + pp; const float ar = apow[(gp * 34 + t + 1) * 2], ai = apow[(gp * 34 + t + 1) * 2 + 1];
;                 const float cr = p.in[23][((size_t)g * 16 + hh) * 64 + pp], ci = p.in[24][((size_t)g * 16 + hh) * 64 + pp]; v[j] = (q < 64) ? (cr * ar - ci * ai) : -(cr * ai + ci * ar); } }
;         u32x4 w; w.x = cvt_pk(v[0], v[1]); w.y = cvt_pk(v[2], v[3]); w.z = cvt_pk(v[4], v[5]); w.w = cvt_pk(v[6], v[7]);
.LBB0_1017:
	s_mov_b32 s2, 0x66666667
	v_mul_hi_i32 v0, v20, s2
	s_waitcnt lgkmcnt(0)
	v_ashrrev_i32_e32 v1, 5, v0
	v_lshrrev_b32_e32 v2, 31, v0
	v_add_u32_e32 v30, v1, v2
	s_movk_i32 s2, 0xffb0
	v_mad_u64_u32 v[28:29], s[2:3], v30, s2, v[20:21]
	v_ashrrev_i32_e32 v0, 14, v0
	s_movk_i32 s2, 0xfd80
	v_add_u32_e32 v24, v0, v2
	v_mad_u64_u32 v[22:23], s[2:3], v30, s2, v[18:19]
	v_bfe_u32 v26, v30, 4, 5
	v_and_b32_e32 v16, 15, v30
	v_cmp_lt_i32_e32 vcc, 63, v28
	v_ashrrev_i32_e32 v25, 31, v24
	s_and_saveexec_b64 s[2:3], vcc
	s_xor_b64 s[2:3], exec, s[2:3]
	s_cbranch_execz .LBB0_1019
	v_lshlrev_b64 v[0:1], 10, v[24:25]
	v_lshlrev_b32_e32 v4, 6, v16
	v_and_b32_e32 v5, 56, v22
	v_lshl_or_b32 v8, v24, 6, v5
	v_or3_b32 v0, v0, v4, v5
	v_readlane_b32 s36, v252, 14
	v_lshlrev_b64 v[4:5], 2, v[0:1]
	v_readlane_b32 s37, v252, 15
	v_readlane_b32 s38, v252, 16
	v_readlane_b32 s39, v252, 17
	v_readlane_b32 s40, v252, 18
	v_readlane_b32 s41, v252, 19
	v_readlane_b32 s42, v252, 20
	v_readlane_b32 s43, v252, 21
	v_readlane_b32 s44, v252, 22
	v_readlane_b32 s45, v252, 23
	v_readlane_b32 s46, v252, 24
	v_readlane_b32 s47, v252, 25
	v_readlane_b32 s48, v252, 26
	v_readlane_b32 s49, v252, 27
	v_readlane_b32 s50, v252, 28
	v_readlane_b32 s51, v252, 29
	s_movk_i32 s4, 0x48
	v_or_b32_e32 v23, 1, v8
	v_mov_b32_e32 v27, v9
	v_mul_hi_i32_i24_e32 v3, 34, v8
	v_mul_i32_i24_e32 v2, 34, v8
	v_lshl_add_u64 v[0:1], s[50:51], 0, v[4:5]
	v_readlane_b32 s36, v251, 40
	v_cmp_gt_u32_e32 vcc, s4, v28
	v_mul_hi_i32_i24_e32 v29, 34, v23
	v_mul_i32_i24_e32 v28, 34, v23
	v_lshl_add_u64 v[2:3], v[2:3], 0, v[26:27]
	v_readlane_b32 s37, v251, 41
	v_lshl_add_u64 v[28:29], v[28:29], 0, v[26:27]
	v_lshl_add_u64 v[32:33], v[2:3], 3, s[56:57]
	v_lshl_add_u64 v[4:5], s[36:37], 0, v[4:5]
	v_lshl_add_u64 v[28:29], v[28:29], 3, s[56:57]
	global_load_dwordx4 v[10:13], v[0:1], off offset:16
	s_nop 0
	global_load_dwordx4 v[0:3], v[0:1], off
	s_nop 0
	global_load_dwordx4 v[14:17], v[4:5], off offset:16
	s_nop 0
	global_load_dwordx4 v[4:7], v[4:5], off
	s_nop 0
	global_load_dwordx2 v[32:33], v[32:33], off offset:8
	s_nop 0
	global_load_dwordx2 v[28:29], v[28:29], off offset:8
	v_or_b32_e32 v60, 2, v8
	v_mul_hi_i32_i24_e32 v61, 34, v60
	v_mul_i32_i24_e32 v60, 34, v60
	v_lshl_add_u64 v[60:61], v[60:61], 0, v[26:27]
	v_lshl_add_u64 v[60:61], v[60:61], 3, s[56:57]
	global_load_dwordx2 v[60:61], v[60:61], off offset:8
	v_or_b32_e32 v62, 3, v8
	v_mul_hi_i32_i24_e32 v63, 34, v62
	v_mul_i32_i24_e32 v62, 34, v62
	v_lshl_add_u64 v[62:63], v[62:63], 0, v[26:27]
	v_lshl_add_u64 v[62:63], v[62:63], 3, s[56:57]
	global_load_dwordx2 v[62:63], v[62:63], off offset:8
	v_or_b32_e32 v64, 4, v8
	v_mul_hi_i32_i24_e32 v65, 34, v64
	v_mul_i32_i24_e32 v64, 34, v64
	v_lshl_add_u64 v[64:65], v[64:65], 0, v[26:27]
	v_lshl_add_u64 v[64:65], v[64:65], 3, s[56:57]
	global_load_dwordx2 v[64:65], v[64:65], off offset:8
	v_or_b32_e32 v66, 5, v8
	v_mul_hi_i32_i24_e32 v67, 34, v66
	v_mul_i32_i24_e32 v66, 34, v66
	v_lshl_add_u64 v[66:67], v[66:67], 0, v[26:27]
	v_lshl_add_u64 v[66:67], v[66:67], 3, s[56:57]
	global_load_dwordx2 v[66:67], v[66:67], off offset:8
	v_or_b32_e32 v68, 6, v8
	v_mul_hi_i32_i24_e32 v69, 34, v68
	v_mul_i32_i24_e32 v68, 34, v68
	v_lshl_add_u64 v[68:69], v[68:69], 0, v[26:27]
	v_lshl_add_u64 v[68:69], v[68:69], 3, s[56:57]
	global_load_dwordx2 v[68:69], v[68:69], off offset:8
	v_or_b32_e32 v70, 7, v8
	v_mul_hi_i32_i24_e32 v71, 34, v70
	v_mul_i32_i24_e32 v70, 34, v70
	v_lshl_add_u64 v[70:71], v[70:71], 0, v[26:27]
	v_lshl_add_u64 v[70:71], v[70:71], 3, s[56:57]
	global_load_dwordx2 v[70:71], v[70:71], off offset:8
	v_readlane_b32 s40, v251, 44
	v_readlane_b32 s38, v251, 42
	v_readlane_b32 s39, v251, 43
	v_readlane_b32 s41, v251, 45
	v_readlane_b32 s42, v251, 46
	v_readlane_b32 s43, v251, 47
	v_readlane_b32 s44, v251, 48
	v_readlane_b32 s45, v251, 49
	v_readlane_b32 s46, v251, 50
	v_readlane_b32 s47, v251, 51
	v_readlane_b32 s48, v251, 52
	v_readlane_b32 s49, v251, 53
	v_readlane_b32 s50, v251, 54
	v_readlane_b32 s51, v251, 55
	v_readlane_b32 s40, v254, 1
	s_waitcnt vmcnt(7)
	v_mov_b32_e32 v34, v32
	s_waitcnt vmcnt(6)
	v_mov_b32_e32 v35, v28
	v_mov_b32_e32 v28, v33
	v_pk_mul_f32 v[32:33], v[28:29], v[4:5]
	v_pk_mul_f32 v[4:5], v[34:35], v[4:5]
	v_pk_fma_f32 v[32:33], v[34:35], v[0:1], v[32:33] neg_lo:[0,0,1] neg_hi:[0,0,1]
	v_pk_fma_f32 v[0:1], v[28:29], v[0:1], v[4:5]
	v_cndmask_b32_e64 v1, -v1, v33, vcc
	v_cndmask_b32_e64 v0, -v0, v32, vcc
	s_waitcnt vmcnt(5)
	v_mov_b32_e32 v4, v60
	v_mov_b32_e32 v5, v61
	v_mov_b32_e32 v32, v4
	s_waitcnt vmcnt(4)
	v_mov_b32_e32 v28, v62
	v_mov_b32_e32 v29, v63
	v_mov_b32_e32 v33, v28
	v_mov_b32_e32 v28, v5
	v_pk_mul_f32 v[4:5], v[28:29], v[6:7]
	v_pk_mul_f32 v[6:7], v[32:33], v[6:7]
	v_pk_fma_f32 v[4:5], v[32:33], v[2:3], v[4:5] neg_lo:[0,0,1] neg_hi:[0,0,1]
	v_pk_fma_f32 v[2:3], v[28:29], v[2:3], v[6:7]
	v_cndmask_b32_e64 v2, -v2, v4, vcc
	v_cndmask_b32_e64 v3, -v3, v5, vcc
	s_waitcnt vmcnt(3)
	v_mov_b32_e32 v4, v64
	v_mov_b32_e32 v5, v65
	v_mov_b32_e32 v28, v4
	s_waitcnt vmcnt(2)
	v_mov_b32_e32 v6, v66
	v_mov_b32_e32 v7, v67
	v_mov_b32_e32 v29, v6
	v_mov_b32_e32 v6, v5
	v_pk_mul_f32 v[4:5], v[6:7], v[14:15]
	v_pk_mul_f32 v[14:15], v[28:29], v[14:15]
	v_pk_fma_f32 v[4:5], v[28:29], v[10:11], v[4:5] neg_lo:[0,0,1] neg_hi:[0,0,1]
	v_pk_fma_f32 v[6:7], v[6:7], v[10:11], v[14:15]
	v_mov_b32_e32 v10, v12
	v_cndmask_b32_e64 v4, -v6, v4, vcc
	v_cndmask_b32_e64 v5, -v7, v5, vcc
	v_mov_b32_e32 v11, v16
	s_waitcnt vmcnt(1)
	v_mov_b32_e32 v6, v68
	v_mov_b32_e32 v7, v69
	v_pk_mul_f32 v[10:11], v[6:7], v[10:11]
	s_nop 0
	v_sub_f32_e32 v14, v10, v11
	v_mov_b32_e32 v10, v16
	v_mov_b32_e32 v11, v12
	v_pk_mul_f32 v[6:7], v[6:7], v[10:11]
	v_mov_b32_e32 v16, v13
	v_add_f32_e32 v6, v7, v6
	v_mov_b32_e32 v12, v17
	v_cndmask_b32_e64 v6, -v6, v14, vcc
	s_waitcnt vmcnt(0)
	v_mov_b32_e32 v10, v70
	v_mov_b32_e32 v11, v71
	v_pk_mul_f32 v[14:15], v[10:11], v[16:17]
	v_pk_mul_f32 v[10:11], v[10:11], v[12:13]
	v_sub_f32_e32 v7, v14, v15
	v_add_f32_e32 v8, v11, v10
	v_cndmask_b32_e64 v7, -v8, v7, vcc
	v_lshlrev_b64 v[10:11], 9, v[24:25]
